# nt hint on the once-read f32 weight/cache loads of the conversion passes (P1 and the up-GEMM filler)
# speedup vs baseline: 1.0188x; 1.0076x over previous
.LBB0_123:
	s_lshr_b32 s31, s46, 5
	v_cvt_f32_u32_e32 v0, s31
	s_sub_i32 s38, 0, s31
	s_abs_i32 s35, s20
	s_ashr_i32 s34, s20, 31
	v_rcp_iflag_f32_e32 v0, v0
	s_nop 0
	v_mul_f32_e32 v0, 0x4f7ffffe, v0
	v_cvt_u32_f32_e32 v0, v0
	s_nop 0
	v_readfirstlane_b32 s39, v0
	s_mul_i32 s38, s38, s39
	s_mul_hi_u32 s38, s39, s38
	s_add_i32 s39, s39, s38
	s_mul_hi_u32 s38, s35, s39
	s_mul_i32 s39, s38, s31
	s_sub_i32 s35, s35, s39
	s_add_i32 s47, s38, 1
	s_sub_i32 s39, s35, s31
	s_cmp_ge_u32 s35, s31
	s_cselect_b32 s38, s47, s38
	s_cselect_b32 s35, s39, s35
	s_add_i32 s39, s38, 1
	s_cmp_ge_u32 s35, s31
	s_cselect_b32 s35, s39, s38
	s_xor_b32 s35, s35, s34
	s_sub_i32 s34, s35, s34
	s_mul_i32 s31, s34, s31
	s_lshl_b32 s38, s34, 6
	s_sub_i32 s20, s20, s31
	v_or_b32_e32 v0, s38, v11
	s_ashr_i32 s39, s38, 31
	s_lshl_b32 s34, s20, 5
	s_mul_i32 s20, s39, s46
	v_mad_u64_u32 v[0:1], s[48:49], v0, s46, 0
	v_add_u32_e32 v1, s20, v1
	v_lshl_add_u64 v[0:1], v[0:1], 2, s[40:41]
	s_ashr_i32 s35, s34, 31
	v_lshl_add_u64 v[0:1], s[34:35], 2, v[0:1]
	v_lshl_add_u64 v[0:1], v[0:1], 0, v[4:5]
	s_lshl_b32 s20, s46, 1
	v_lshl_add_u64 v[2:3], s[20:21], 2, v[0:1]
	s_lshl_b32 s20, s46, 2
	v_lshl_add_u64 v[8:9], s[20:21], 2, v[0:1]
	s_mul_i32 s20, s46, 6
	v_lshl_add_u64 v[30:31], s[20:21], 2, v[0:1]
	s_lshl_b32 s20, s46, 3
	v_lshl_add_u64 v[32:33], s[20:21], 2, v[0:1]
	s_mul_i32 s20, s46, 10
	v_lshl_add_u64 v[34:35], s[20:21], 2, v[0:1]
	s_mul_i32 s20, s46, 12
	v_lshl_add_u64 v[36:37], s[20:21], 2, v[0:1]
	s_mul_i32 s20, s46, 14
	v_lshl_add_u64 v[38:39], s[20:21], 2, v[0:1]
	s_lshl_b32 s20, s46, 4
	global_load_dword v42, v[0:1], off nt
	global_load_dword v43, v[2:3], off nt
	global_load_dword v44, v[8:9], off nt
	global_load_dword v45, v[30:31], off nt
	global_load_dword v46, v[32:33], off nt
	global_load_dword v47, v[34:35], off nt
	global_load_dword v48, v[36:37], off nt
	global_load_dword v49, v[38:39], off nt
	v_lshl_add_u64 v[2:3], s[20:21], 2, v[0:1]
	s_mul_i32 s20, s46, 18
	v_lshl_add_u64 v[8:9], s[20:21], 2, v[0:1]
	s_mul_i32 s20, s46, 20
	v_lshl_add_u64 v[30:31], s[20:21], 2, v[0:1]
	s_mul_i32 s20, s46, 22
	v_lshl_add_u64 v[32:33], s[20:21], 2, v[0:1]
	s_mul_i32 s20, s46, 24
	v_lshl_add_u64 v[34:35], s[20:21], 2, v[0:1]
	s_mul_i32 s20, s46, 26
	v_lshl_add_u64 v[36:37], s[20:21], 2, v[0:1]
	s_mul_i32 s20, s46, 28
	v_lshl_add_u64 v[38:39], s[20:21], 2, v[0:1]
	s_mul_i32 s20, s46, 30
	v_lshl_add_u64 v[40:41], s[20:21], 2, v[0:1]
	s_lshl_b32 s20, s46, 5
	global_load_dword v50, v[2:3], off nt
	global_load_dword v51, v[8:9], off nt
	global_load_dword v52, v[30:31], off nt
	global_load_dword v53, v[32:33], off nt
	global_load_dword v54, v[34:35], off nt
	global_load_dword v55, v[36:37], off nt
	global_load_dword v56, v[38:39], off nt
	global_load_dword v57, v[40:41], off nt
	v_lshl_add_u64 v[2:3], s[20:21], 2, v[0:1]
	s_mul_i32 s20, s46, 34
	v_lshl_add_u64 v[8:9], s[20:21], 2, v[0:1]
	s_mul_i32 s20, s46, 36
	v_lshl_add_u64 v[30:31], s[20:21], 2, v[0:1]
	s_mul_i32 s20, s46, 38
	v_lshl_add_u64 v[32:33], s[20:21], 2, v[0:1]
	s_mul_i32 s20, s46, 40
	v_lshl_add_u64 v[34:35], s[20:21], 2, v[0:1]
	s_mul_i32 s20, s46, 42
	v_lshl_add_u64 v[36:37], s[20:21], 2, v[0:1]
	s_mul_i32 s20, s46, 44
	v_lshl_add_u64 v[38:39], s[20:21], 2, v[0:1]
	s_mul_i32 s20, s46, 46
	v_lshl_add_u64 v[40:41], s[20:21], 2, v[0:1]
	s_mul_i32 s20, s46, 48
	global_load_dword v58, v[2:3], off nt
	global_load_dword v59, v[8:9], off nt
	global_load_dword v60, v[30:31], off nt
	global_load_dword v61, v[32:33], off nt
	global_load_dword v62, v[34:35], off nt
	global_load_dword v63, v[36:37], off nt
	global_load_dword v64, v[38:39], off nt
	global_load_dword v65, v[40:41], off nt
	v_lshl_add_u64 v[2:3], s[20:21], 2, v[0:1]
	s_mul_i32 s20, s46, 50
	v_lshl_add_u64 v[8:9], s[20:21], 2, v[0:1]
	s_mul_i32 s20, s46, 52
	v_lshl_add_u64 v[30:31], s[20:21], 2, v[0:1]
	s_mul_i32 s20, s46, 54
	v_lshl_add_u64 v[32:33], s[20:21], 2, v[0:1]
	s_mul_i32 s20, s46, 56
	v_lshl_add_u64 v[34:35], s[20:21], 2, v[0:1]
	s_mul_i32 s20, s46, 58
	v_lshl_add_u64 v[36:37], s[20:21], 2, v[0:1]
	s_mul_i32 s20, s46, 60
	v_lshl_add_u64 v[38:39], s[20:21], 2, v[0:1]
	s_mul_i32 s20, s46, 62
	v_lshl_add_u64 v[0:1], s[20:21], 2, v[0:1]
	global_load_dword v40, v[2:3], off nt
	global_load_dword v41, v[8:9], off nt
	global_load_dword v66, v[30:31], off nt
	global_load_dword v67, v[32:33], off nt
	global_load_dword v68, v[34:35], off nt
	global_load_dword v69, v[36:37], off nt
	global_load_dword v70, v[38:39], off nt
	global_load_dword v71, v[0:1], off nt
	s_lshr_b32 s20, s34, 3
	s_cmp_gt_i32 s45, 1
	s_mov_b64 s[40:41], -1
	s_waitcnt vmcnt(30)
	ds_write2_b32 v21, v42, v43 offset1:66
	s_waitcnt vmcnt(28)
	ds_write2_b32 v21, v44, v45 offset0:132 offset1:198
	s_waitcnt vmcnt(26)
	ds_write2_b32 v23, v46, v47 offset0:8 offset1:74
	s_waitcnt vmcnt(24)
	ds_write2_b32 v23, v48, v49 offset0:140 offset1:206
	s_waitcnt vmcnt(22)
	ds_write2_b32 v24, v50, v51 offset0:16 offset1:82
	s_waitcnt vmcnt(20)
	ds_write2_b32 v24, v52, v53 offset0:148 offset1:214
	s_waitcnt vmcnt(18)
	ds_write2_b32 v25, v54, v55 offset0:24 offset1:90
	s_waitcnt vmcnt(16)
	ds_write2_b32 v25, v56, v57 offset0:156 offset1:222
	s_waitcnt vmcnt(14)
	ds_write2_b32 v26, v58, v59 offset0:32 offset1:98
	s_waitcnt vmcnt(12)
	ds_write2_b32 v26, v60, v61 offset0:164 offset1:230
	s_waitcnt vmcnt(10)
	ds_write2_b32 v27, v62, v63 offset0:40 offset1:106
	s_waitcnt vmcnt(8)
	ds_write2_b32 v27, v64, v65 offset0:172 offset1:238
	s_waitcnt vmcnt(6)
	ds_write2_b32 v28, v40, v41 offset0:48 offset1:114
	s_waitcnt vmcnt(4)
	ds_write2_b32 v28, v66, v67 offset0:180 offset1:246
	s_waitcnt vmcnt(2)
	ds_write2_b32 v29, v68, v69 offset0:56 offset1:122
	s_waitcnt vmcnt(0)
	ds_write2_b32 v29, v70, v71 offset0:188 offset1:254
	s_waitcnt lgkmcnt(0)
	ds_read2_b32 v[0:1], v13 offset1:33
	s_waitcnt lgkmcnt(0)
	v_cvt_pk_bf16_f32 v0, v0, v1
	ds_read2_b32 v[2:3], v13 offset0:66 offset1:99
	s_waitcnt lgkmcnt(0)
	v_cvt_pk_bf16_f32 v1, v2, v3
	ds_read2_b32 v[2:3], v13 offset0:132 offset1:165
	s_waitcnt lgkmcnt(0)
	v_cvt_pk_bf16_f32 v2, v2, v3
	ds_read2_b32 v[8:9], v13 offset0:198 offset1:231
	s_waitcnt lgkmcnt(0)
	v_cvt_pk_bf16_f32 v3, v8, v9
	v_bitop3_b32 v8, s34, v22, v12 bitop3:0xc8
	v_and_or_b32 v30, s20, 4, v8
	s_cbranch_scc0 .LBB0_125
	v_or_b32_e32 v31, v30, v14
	s_mov_b64 s[40:41], 0

.LBB0_153:
	s_bfe_u32 s17, s42, 0x20009
	s_ashr_i32 s16, s42, 11
	s_lshl_b32 s14, s17, 1
	s_add_i32 s14, s14, s16
	s_and_b32 s18, s42, 0x1ff
	s_ashr_i32 s15, s14, 31
	s_lshl_b32 s19, s18, 8
	s_lshl_b64 s[14:15], s[14:15], 17
	s_or_b32 s14, s14, s19
	v_mov_b32_e32 v3, s15
	v_or_b32_e32 v2, s14, v0
	v_lshlrev_b64 v[2:3], 2, v[2:3]
	v_lshl_add_u64 v[10:11], s[4:5], 0, v[2:3]
	v_lshl_add_u64 v[12:13], s[6:7], 0, v[2:3]
	global_load_dwordx4 v[2:5], v[10:11], off nt
	global_load_dwordx4 v[6:9], v[12:13], off nt
	s_mulk_i32 s17, 0xa00
	s_or_b32 s14, s17, s18
	s_lshl_b32 s14, s14, 8
	s_mul_hi_i32 s19, s16, 0x500000
	s_mul_i32 s16, s16, 0x500000
	s_add_i32 s14, s14, 0x80000
	v_or_b32_e32 v1, s14, v0
	s_add_u32 s14, s12, s16
	s_addc_u32 s15, s13, s19
	s_add_u32 s16, s2, s16
	s_addc_u32 s17, s3, s19
	s_add_i32 s42, s42, s33
	v_lshlrev_b32_e32 v1, 1, v1
	s_cmpk_lt_i32 s42, 0x1000
	s_waitcnt vmcnt(1)
	v_cvt_pk_bf16_f32 v2, v2, v3
	v_cvt_pk_bf16_f32 v3, v4, v5
	s_waitcnt vmcnt(0)
	v_cvt_pk_bf16_f32 v4, v6, v7
	v_cvt_pk_bf16_f32 v5, v8, v9
	global_store_dwordx2 v1, v[2:3], s[14:15]
	global_store_dwordx2 v1, v[4:5], s[16:17]
	s_cbranch_scc1 .LBB0_153

.LBB0_766:
	s_lshr_b32 s30, s78, 5
	v_cvt_f32_u32_e32 v0, s30
	s_sub_i32 s69, 0, s30
	s_abs_i32 s68, s72
	s_ashr_i32 s31, s72, 31
	v_rcp_iflag_f32_e32 v0, v0
	s_nop 0
	v_mul_f32_e32 v0, 0x4f7ffffe, v0
	v_cvt_u32_f32_e32 v0, v0
	s_nop 0
	v_readfirstlane_b32 s73, v0
	s_mul_i32 s69, s69, s73
	s_mul_hi_u32 s69, s73, s69
	s_add_i32 s73, s73, s69
	s_mul_hi_u32 s69, s68, s73
	s_mul_i32 s73, s69, s30
	s_sub_i32 s68, s68, s73
	s_add_i32 s73, s69, 1
	s_sub_i32 s79, s68, s30
	s_cmp_ge_u32 s68, s30
	s_cselect_b32 s69, s73, s69
	s_cselect_b32 s68, s79, s68
	s_add_i32 s73, s69, 1
	s_cmp_ge_u32 s68, s30
	s_cselect_b32 s68, s73, s69
	s_xor_b32 s68, s68, s31
	s_sub_i32 s31, s68, s31
	s_mul_i32 s30, s31, s30
	s_sub_i32 s30, s72, s30
	s_lshl_b32 s72, s31, 6
	v_or_b32_e32 v0, s72, v8
	s_ashr_i32 s73, s72, 31
	s_lshl_b32 s68, s30, 5
	s_mul_i32 s69, s73, s78
	v_mad_u64_u32 v[0:1], s[30:31], v0, s78, 0
	v_add_u32_e32 v1, s69, v1
	v_lshl_add_u64 v[0:1], v[0:1], 2, s[74:75]
	s_ashr_i32 s69, s68, 31
	v_lshl_add_u64 v[0:1], s[68:69], 2, v[0:1]
	v_lshl_add_u64 v[0:1], v[0:1], 0, v[96:97]
	s_lshl_b32 s30, s78, 1
	s_mov_b32 s31, s12
	v_lshl_add_u64 v[2:3], s[30:31], 2, v[0:1]
	s_lshl_b32 s30, s78, 2
	global_load_dword v5, v[0:1], off nt
	global_load_dword v6, v[2:3], off nt
	v_lshl_add_u64 v[2:3], s[30:31], 2, v[0:1]
	s_mul_i32 s30, s78, 6
	global_load_dword v7, v[2:3], off nt
	v_lshl_add_u64 v[2:3], s[30:31], 2, v[0:1]
	s_lshl_b32 s30, s78, 3
	global_load_dword v19, v[2:3], off nt
	v_lshl_add_u64 v[2:3], s[30:31], 2, v[0:1]
	s_mul_i32 s30, s78, 10
	global_load_dword v20, v[2:3], off nt
	v_lshl_add_u64 v[2:3], s[30:31], 2, v[0:1]
	s_mul_i32 s30, s78, 12
	global_load_dword v21, v[2:3], off nt
	v_lshl_add_u64 v[2:3], s[30:31], 2, v[0:1]
	s_mul_i32 s30, s78, 14
	global_load_dword v22, v[2:3], off nt
	v_lshl_add_u64 v[2:3], s[30:31], 2, v[0:1]
	s_lshl_b32 s30, s78, 4
	global_load_dword v23, v[2:3], off nt
	v_lshl_add_u64 v[2:3], s[30:31], 2, v[0:1]
	s_mul_i32 s30, s78, 18
	global_load_dword v24, v[2:3], off nt
	v_lshl_add_u64 v[2:3], s[30:31], 2, v[0:1]
	s_mul_i32 s30, s78, 20
	global_load_dword v25, v[2:3], off nt
	v_lshl_add_u64 v[2:3], s[30:31], 2, v[0:1]
	s_mul_i32 s30, s78, 22
	global_load_dword v26, v[2:3], off nt
	v_lshl_add_u64 v[2:3], s[30:31], 2, v[0:1]
	s_mul_i32 s30, s78, 24
	global_load_dword v27, v[2:3], off nt
	v_lshl_add_u64 v[2:3], s[30:31], 2, v[0:1]
	s_mul_i32 s30, s78, 26
	global_load_dword v28, v[2:3], off nt
	v_lshl_add_u64 v[2:3], s[30:31], 2, v[0:1]
	s_mul_i32 s30, s78, 28
	global_load_dword v29, v[2:3], off nt
	v_lshl_add_u64 v[2:3], s[30:31], 2, v[0:1]
	s_mul_i32 s30, s78, 30
	global_load_dword v30, v[2:3], off nt
	v_lshl_add_u64 v[2:3], s[30:31], 2, v[0:1]
	s_lshl_b32 s30, s78, 5
	global_load_dword v31, v[2:3], off nt
	v_lshl_add_u64 v[2:3], s[30:31], 2, v[0:1]
	s_mul_i32 s30, s78, 34
	global_load_dword v32, v[2:3], off nt
	v_lshl_add_u64 v[2:3], s[30:31], 2, v[0:1]
	s_mul_i32 s30, s78, 36
	global_load_dword v33, v[2:3], off nt
	v_lshl_add_u64 v[2:3], s[30:31], 2, v[0:1]
	s_mul_i32 s30, s78, 38
	global_load_dword v34, v[2:3], off nt
	v_lshl_add_u64 v[2:3], s[30:31], 2, v[0:1]
	s_mul_i32 s30, s78, 40
	global_load_dword v35, v[2:3], off nt
	v_lshl_add_u64 v[2:3], s[30:31], 2, v[0:1]
	s_mul_i32 s30, s78, 42
	global_load_dword v36, v[2:3], off nt
	v_lshl_add_u64 v[2:3], s[30:31], 2, v[0:1]
	s_mul_i32 s30, s78, 44
	global_load_dword v37, v[2:3], off nt
	v_lshl_add_u64 v[2:3], s[30:31], 2, v[0:1]
	s_mul_i32 s30, s78, 46
	global_load_dword v38, v[2:3], off nt
	v_lshl_add_u64 v[2:3], s[30:31], 2, v[0:1]
	s_mul_i32 s30, s78, 48
	global_load_dword v39, v[2:3], off nt
	v_lshl_add_u64 v[2:3], s[30:31], 2, v[0:1]
	s_mul_i32 s30, s78, 50
	global_load_dword v40, v[2:3], off nt
	v_lshl_add_u64 v[2:3], s[30:31], 2, v[0:1]
	s_mul_i32 s30, s78, 52
	global_load_dword v41, v[2:3], off nt
	v_lshl_add_u64 v[2:3], s[30:31], 2, v[0:1]
	s_mul_i32 s30, s78, 54
	global_load_dword v42, v[2:3], off nt
	v_lshl_add_u64 v[2:3], s[30:31], 2, v[0:1]
	s_mul_i32 s30, s78, 56
	global_load_dword v43, v[2:3], off nt
	v_lshl_add_u64 v[2:3], s[30:31], 2, v[0:1]
	s_mul_i32 s30, s78, 58
	global_load_dword v44, v[2:3], off nt
	v_lshl_add_u64 v[2:3], s[30:31], 2, v[0:1]
	s_mul_i32 s30, s78, 60
	global_load_dword v45, v[2:3], off nt
	v_lshl_add_u64 v[2:3], s[30:31], 2, v[0:1]
	s_mul_i32 s30, s78, 62
	v_lshl_add_u64 v[0:1], s[30:31], 2, v[0:1]
	global_load_dword v2, v[2:3], off nt
	s_lshr_b32 s30, s68, 3
	global_load_dword v0, v[0:1], off nt
	v_add_u32_e32 v1, 0x400, v18
	s_waitcnt vmcnt(0)
	ds_write2_b32 v18, v5, v6 offset1:66
	ds_write2_b32 v18, v7, v19 offset0:132 offset1:198
	ds_write2_b32 v1, v20, v21 offset0:8 offset1:74
	ds_write2_b32 v1, v22, v23 offset0:140 offset1:206
	v_add_u32_e32 v1, 0x800, v18
	ds_write2_b32 v1, v24, v25 offset0:16 offset1:82
	ds_write2_b32 v1, v26, v27 offset0:148 offset1:214
	v_add_u32_e32 v1, 0xc00, v18
	ds_write2_b32 v1, v28, v29 offset0:24 offset1:90
	ds_write2_b32 v1, v30, v31 offset0:156 offset1:222
	v_add_u32_e32 v1, 0x1000, v18
	ds_write2_b32 v1, v32, v33 offset0:32 offset1:98
	ds_write2_b32 v1, v34, v35 offset0:164 offset1:230
	v_add_u32_e32 v1, 0x1400, v18
	ds_write2_b32 v1, v36, v37 offset0:40 offset1:106
	ds_write2_b32 v1, v38, v39 offset0:172 offset1:238
	v_add_u32_e32 v1, 0x1800, v18
	ds_write2_b32 v1, v40, v41 offset0:48 offset1:114
	ds_write2_b32 v1, v42, v43 offset0:180 offset1:246
	v_add_u32_e32 v1, 0x1c00, v18
	ds_write2_b32 v1, v44, v45 offset0:56 offset1:122
	ds_write2_b32 v1, v2, v0 offset0:188 offset1:254
	s_waitcnt lgkmcnt(0)
	ds_read2_b32 v[0:1], v10 offset1:33
	v_not_b32_e32 v5, 60
	s_waitcnt lgkmcnt(0)
	v_cvt_pk_bf16_f32 v0, v0, v1
	ds_read2_b32 v[2:3], v10 offset0:66 offset1:99
	v_bitop3_b32 v5, s68, v5, v9 bitop3:0xc8
	s_waitcnt lgkmcnt(0)
	v_cvt_pk_bf16_f32 v1, v2, v3
	ds_read2_b32 v[2:3], v10 offset0:132 offset1:165
	v_and_or_b32 v19, s30, 4, v5
	s_cmp_gt_i32 s77, 1
	s_mov_b64 s[74:75], -1
	s_waitcnt lgkmcnt(0)
	v_cvt_pk_bf16_f32 v2, v2, v3
	ds_read2_b32 v[6:7], v10 offset0:198 offset1:231
	s_waitcnt lgkmcnt(0)
	v_cvt_pk_bf16_f32 v3, v6, v7
	s_cbranch_scc0 .LBB0_768
	v_or_b32_e32 v20, v19, v11
	s_mov_b64 s[74:75], 0
